# GEMM K-loop 4-phase with SADDR-form LDS-DMA (scalar pointer arithmetic, no 64-bit VALU address adds)
# baseline (speedup 1.0000x reference)
; #define PG8_STAGE(bufoff, gbase, voff) do { _Pragma("unroll") for (int _i = 0; _i < 2; ++_i) \
;     __builtin_amdgcn_global_load_lds((const unsigned*)((const char*)(gbase) + (voff)[_i]), (LAS unsigned*)(lds + (bufoff) + ldsw + _i * 8192), 16, 0, 0); } while (0)
; #define PG8_LDA(dst, b, h) do { _Pragma("unroll") for (int m = 0; m < 4; ++m) _Pragma("unroll") for (int k = 0; k < 2; ++k) dst[m][k] = *(const LAS bf16x8*)(lds + PG8_SA(b, h) + aoff + m * 2048 + k * 1024); } while (0)
; #define PG8_LDB(dst, b, h) do { _Pragma("unroll") for (int n = 0; n < 2; ++n) _Pragma("unroll") for (int k = 0; k < 2; ++k) dst[n][k] = *(const LAS bf16x8*)(lds + PG8_SB(b, h) + boff + n * 2048 + k * 1024); } while (0)
; #define PG8_MMA(ai, bj, At, Bt) do { __builtin_amdgcn_s_setprio(1); _Pragma("unroll") for (int m = 0; m < 4; ++m) _Pragma("unroll") for (int n = 0; n < 2; ++n) _Pragma("unroll") for (int k = 0; k < 2; ++k) \
;     acc[ai][bj][m][n] = __builtin_amdgcn_mfma_f32_16x16x32_bf16(Bt[n][k], At[m][k], acc[ai][bj][m][n], 0, 0, 0); __builtin_amdgcn_s_setprio(0); } while (0)
; #define PG8_WAIT_V(n) asm volatile("s_waitcnt vmcnt(" #n ")" ::: "memory")
; #define PG8_WAIT_L(n) asm volatile("s_waitcnt lgkmcnt(" #n ")" ::: "memory")
; #define PG8_BAR __builtin_amdgcn_s_barrier()
; #define PG8_SCHED __builtin_amdgcn_sched_barrier(0)
; template <class Epi>
; __device__ __forceinline__ void gemm_phase(LAS unsigned char* lds, const Gemm g, const StaticOrder& S, const Epi& E) {
;     ...
;       PG8_LDB(B0, 0, 0); PG8_SCHED; PG8_LDA(At, 0, 0); PG8_STAGE(PG8_SA(1, 1), a1 + hstep, voffA);
;       PG8_WAIT_L(8); PG8_BAR; PG8_WAIT_L(0); PG8_MMA(0, 0, At, B0); PG8_BAR; PG8_SCHED;
;       PG8_LDB(B1, 0, 1); PG8_STAGE(PG8_SB(0, 0), b2, voffB);
;       PG8_BAR; PG8_WAIT_L(0); PG8_MMA(0, 1, At, B1); PG8_BAR;
;       PG8_LDA(At, 0, 1); PG8_STAGE(PG8_SA(0, 0), a2, voffA);
;       PG8_BAR; PG8_WAIT_L(0); PG8_MMA(1, 0, At, B0); PG8_BAR; PG8_SCHED;
;       PG8_STAGE(PG8_SB(0, 1), b2 + hstep, voffB);
;       PG8_WAIT_V(6); PG8_BAR; PG8_MMA(1, 1, At, B1); PG8_BAR;
.LBB0_56:
	s_add_i32 s76, s10, 2
	s_add_u32 s12, s0, 0x80
	s_addc_u32 s11, s1, 0
	v_add_u32_e32 v80, 0x10000, v187
	ds_read_b128 v[130:133], v80
	ds_read_b128 v[134:137], v80 offset:1024
	ds_read_b128 v[138:141], v80 offset:2048
	ds_read_b128 v[142:145], v80 offset:3072
	s_cmp_eq_u32 s21, s10
	s_cselect_b32 s10, s18, s12
	s_cselect_b32 s11, s19, s11
	s_cselect_b32 s13, s17, s75
	s_cselect_b32 s12, s16, s74
	s_add_u32 vcc_lo, s0, s64
	s_addc_u32 vcc_hi, s1, 0
	s_add_i32 m0, s15, 0xc000
	ds_read_b128 v[146:149], v189
	ds_read_b128 v[150:153], v189 offset:1024
	ds_read_b128 v[154:157], v189 offset:2048
	ds_read_b128 v[158:161], v189 offset:3072
	ds_read_b128 v[174:177], v189 offset:4096
	ds_read_b128 v[178:181], v189 offset:5120
	ds_read_b128 v[182:185], v189 offset:6144
	ds_read_b128 v[190:193], v189 offset:7168
	global_load_lds_dwordx4 v162, vcc
	s_add_i32 m0, s15, 0xe000
	ds_read_b128 v[194:197], v80 offset:16384
	ds_read_b128 v[198:201], v80 offset:17408
	ds_read_b128 v[202:205], v80 offset:18432
	ds_read_b128 v[206:209], v80 offset:19456
	global_load_lds_dwordx4 v166, vcc
	s_cmp_lg_u32 s76, 2
	s_waitcnt lgkmcnt(0)
	s_cbranch_scc0 .Lkq1
	s_waitcnt vmcnt(8)
.Lkq1:
	s_barrier
	v_mfma_f32_16x16x32_bf16 v[126:129], v[130:133], v[146:149], v[126:129]
	v_mfma_f32_16x16x32_bf16 v[122:125], v[138:141], v[146:149], v[122:125]
	v_mfma_f32_16x16x32_bf16 v[118:121], v[130:133], v[154:157], v[118:121]
	v_mfma_f32_16x16x32_bf16 v[114:117], v[138:141], v[154:157], v[114:117]
	v_mfma_f32_16x16x32_bf16 v[110:113], v[130:133], v[174:177], v[110:113]
	v_mfma_f32_16x16x32_bf16 v[106:109], v[138:141], v[174:177], v[106:109]
	v_mfma_f32_16x16x32_bf16 v[102:105], v[130:133], v[182:185], v[102:105]
	v_mfma_f32_16x16x32_bf16 v[98:101], v[138:141], v[182:185], v[98:101]
	v_mfma_f32_16x16x32_bf16 v[126:129], v[134:137], v[150:153], v[126:129]
	v_mfma_f32_16x16x32_bf16 v[122:125], v[142:145], v[150:153], v[122:125]
	v_mfma_f32_16x16x32_bf16 v[118:121], v[134:137], v[158:161], v[118:121]
	v_mfma_f32_16x16x32_bf16 v[114:117], v[142:145], v[158:161], v[114:117]
	v_mfma_f32_16x16x32_bf16 v[110:113], v[134:137], v[178:181], v[110:113]
	v_mfma_f32_16x16x32_bf16 v[106:109], v[142:145], v[178:181], v[106:109]
	v_mfma_f32_16x16x32_bf16 v[102:105], v[134:137], v[190:193], v[102:105]
	v_mfma_f32_16x16x32_bf16 v[98:101], v[142:145], v[190:193], v[98:101]
	v_mfma_f32_16x16x32_bf16 v[60:63], v[194:197], v[146:149], v[60:63]
	v_mfma_f32_16x16x32_bf16 v[56:59], v[202:205], v[146:149], v[56:59]
	v_mfma_f32_16x16x32_bf16 v[52:55], v[194:197], v[154:157], v[52:55]
	v_mfma_f32_16x16x32_bf16 v[48:51], v[202:205], v[154:157], v[48:51]
	v_mfma_f32_16x16x32_bf16 v[44:47], v[194:197], v[174:177], v[44:47]
	v_mfma_f32_16x16x32_bf16 v[40:43], v[202:205], v[174:177], v[40:43]
	v_mfma_f32_16x16x32_bf16 v[36:39], v[194:197], v[182:185], v[36:39]
	v_mfma_f32_16x16x32_bf16 v[32:35], v[202:205], v[182:185], v[32:35]
	v_mfma_f32_16x16x32_bf16 v[60:63], v[198:201], v[150:153], v[60:63]
	v_mfma_f32_16x16x32_bf16 v[56:59], v[206:209], v[150:153], v[56:59]
	v_mfma_f32_16x16x32_bf16 v[52:55], v[198:201], v[158:161], v[52:55]
	v_mfma_f32_16x16x32_bf16 v[48:51], v[206:209], v[158:161], v[48:51]
	v_mfma_f32_16x16x32_bf16 v[44:47], v[198:201], v[178:181], v[44:47]
	v_mfma_f32_16x16x32_bf16 v[40:43], v[206:209], v[178:181], v[40:43]
	v_mfma_f32_16x16x32_bf16 v[36:39], v[198:201], v[190:193], v[36:39]
	v_mfma_f32_16x16x32_bf16 v[32:35], v[206:209], v[190:193], v[32:35]
	s_barrier
	ds_read_b128 v[146:149], v189 offset:16384
	ds_read_b128 v[150:153], v189 offset:17408
	ds_read_b128 v[154:157], v189 offset:18432
	ds_read_b128 v[158:161], v189 offset:19456
	ds_read_b128 v[174:177], v189 offset:20480
	ds_read_b128 v[178:181], v189 offset:21504
	ds_read_b128 v[182:185], v189 offset:22528
	ds_read_b128 v[190:193], v189 offset:23552
	s_add_i32 m0, s14, 0x10000
	s_add_u32 vcc_lo, s12, s64
	s_addc_u32 vcc_hi, s13, 0
	global_load_lds_dwordx4 v164, s[12:13]
	s_add_i32 m0, s14, 0x12000
	s_nop 0
	global_load_lds_dwordx4 v168, s[12:13]
	s_mov_b32 m0, s15
	s_nop 0
	global_load_lds_dwordx4 v162, s[10:11]
	s_mov_b32 m0, s84
	s_nop 0
	global_load_lds_dwordx4 v166, s[10:11]
	s_add_i32 m0, s14, 0x14000
	s_nop 0
	global_load_lds_dwordx4 v164, vcc
	s_add_i32 m0, s14, 0x16000
	s_cmp_lg_u32 s76, 2
	global_load_lds_dwordx4 v168, vcc
	s_waitcnt lgkmcnt(0)
	s_cbranch_scc0 .Lkq2
	s_waitcnt vmcnt(8)
; #define PG8_STAGE(bufoff, gbase, voff) do { _Pragma("unroll") for (int _i = 0; _i < 2; ++_i) \
;     __builtin_amdgcn_global_load_lds((const unsigned*)((const char*)(gbase) + (voff)[_i]), (LAS unsigned*)(lds + (bufoff) + ldsw + _i * 8192), 16, 0, 0); } while (0)
; #define PG8_LDA(dst, b, h) do { _Pragma("unroll") for (int m = 0; m < 4; ++m) _Pragma("unroll") for (int k = 0; k < 2; ++k) dst[m][k] = *(const LAS bf16x8*)(lds + PG8_SA(b, h) + aoff + m * 2048 + k * 1024); } while (0)
; #define PG8_LDB(dst, b, h) do { _Pragma("unroll") for (int n = 0; n < 2; ++n) _Pragma("unroll") for (int k = 0; k < 2; ++k) dst[n][k] = *(const LAS bf16x8*)(lds + PG8_SB(b, h) + boff + n * 2048 + k * 1024); } while (0)
; #define PG8_MMA(ai, bj, At, Bt) do { __builtin_amdgcn_s_setprio(1); _Pragma("unroll") for (int m = 0; m < 4; ++m) _Pragma("unroll") for (int n = 0; n < 2; ++n) _Pragma("unroll") for (int k = 0; k < 2; ++k) \
;     acc[ai][bj][m][n] = __builtin_amdgcn_mfma_f32_16x16x32_bf16(Bt[n][k], At[m][k], acc[ai][bj][m][n], 0, 0, 0); __builtin_amdgcn_s_setprio(0); } while (0)
; #define PG8_WAIT_V(n) asm volatile("s_waitcnt vmcnt(" #n ")" ::: "memory")
; #define PG8_WAIT_L(n) asm volatile("s_waitcnt lgkmcnt(" #n ")" ::: "memory")
; #define PG8_BAR __builtin_amdgcn_s_barrier()
; #define PG8_SCHED __builtin_amdgcn_sched_barrier(0)
; template <class Epi>
; __device__ __forceinline__ void gemm_phase(LAS unsigned char* lds, const Gemm g, const StaticOrder& S, const Epi& E) {
;     ...
;       PG8_LDA(At, 0, 1); PG8_STAGE(PG8_SA(0, 0), a2, voffA);
;       PG8_BAR; PG8_WAIT_L(0); PG8_MMA(1, 0, At, B0); PG8_BAR; PG8_SCHED;
;       PG8_STAGE(PG8_SB(0, 1), b2 + hstep, voffB);
;       PG8_WAIT_V(6); PG8_BAR; PG8_MMA(1, 1, At, B1); PG8_BAR;
;       PG8_LDB(B0, 1, 0); PG8_SCHED; PG8_LDA(At, 1, 0); PG8_STAGE(PG8_SA(0, 1), a2 + hstep, voffA);
;       PG8_WAIT_L(8); PG8_BAR; PG8_WAIT_L(0); PG8_MMA(0, 0, At, B0); PG8_BAR; PG8_SCHED;
;       PG8_LDB(B1, 1, 1); PG8_STAGE(PG8_SB(1, 0), b3, voffB);
;       PG8_BAR; PG8_WAIT_L(0); PG8_MMA(0, 1, At, B1); PG8_BAR;
.Lkq2:
	s_barrier
	v_mfma_f32_16x16x32_bf16 v[94:97], v[130:133], v[146:149], v[94:97]
	v_mfma_f32_16x16x32_bf16 v[90:93], v[138:141], v[146:149], v[90:93]
	v_mfma_f32_16x16x32_bf16 v[86:89], v[130:133], v[154:157], v[86:89]
	v_mfma_f32_16x16x32_bf16 v[82:85], v[138:141], v[154:157], v[82:85]
	v_mfma_f32_16x16x32_bf16 v[76:79], v[130:133], v[174:177], v[76:79]
	v_mfma_f32_16x16x32_bf16 v[72:75], v[138:141], v[174:177], v[72:75]
	v_mfma_f32_16x16x32_bf16 v[68:71], v[130:133], v[182:185], v[68:71]
	v_mfma_f32_16x16x32_bf16 v[64:67], v[138:141], v[182:185], v[64:67]
	v_mfma_f32_16x16x32_bf16 v[94:97], v[134:137], v[150:153], v[94:97]
	v_mfma_f32_16x16x32_bf16 v[90:93], v[142:145], v[150:153], v[90:93]
	v_mfma_f32_16x16x32_bf16 v[86:89], v[134:137], v[158:161], v[86:89]
	v_mfma_f32_16x16x32_bf16 v[82:85], v[142:145], v[158:161], v[82:85]
	v_mfma_f32_16x16x32_bf16 v[76:79], v[134:137], v[178:181], v[76:79]
	v_mfma_f32_16x16x32_bf16 v[72:75], v[142:145], v[178:181], v[72:75]
	v_mfma_f32_16x16x32_bf16 v[68:71], v[134:137], v[190:193], v[68:71]
	v_mfma_f32_16x16x32_bf16 v[64:67], v[142:145], v[190:193], v[64:67]
	v_mfma_f32_16x16x32_bf16 v[28:31], v[194:197], v[146:149], v[28:31]
	v_mfma_f32_16x16x32_bf16 v[24:27], v[202:205], v[146:149], v[24:27]
	v_mfma_f32_16x16x32_bf16 v[20:23], v[194:197], v[154:157], v[20:23]
	v_mfma_f32_16x16x32_bf16 v[16:19], v[202:205], v[154:157], v[16:19]
	v_mfma_f32_16x16x32_bf16 v[12:15], v[194:197], v[174:177], v[12:15]
	v_mfma_f32_16x16x32_bf16 v[8:11], v[202:205], v[174:177], v[8:11]
	v_mfma_f32_16x16x32_bf16 v[4:7], v[194:197], v[182:185], v[4:7]
	v_mfma_f32_16x16x32_bf16 v[0:3], v[202:205], v[182:185], v[0:3]
	v_mfma_f32_16x16x32_bf16 v[28:31], v[198:201], v[150:153], v[28:31]
	v_mfma_f32_16x16x32_bf16 v[24:27], v[206:209], v[150:153], v[24:27]
	v_mfma_f32_16x16x32_bf16 v[20:23], v[198:201], v[158:161], v[20:23]
	v_mfma_f32_16x16x32_bf16 v[16:19], v[206:209], v[158:161], v[16:19]
	v_mfma_f32_16x16x32_bf16 v[12:15], v[198:201], v[178:181], v[12:15]
	v_mfma_f32_16x16x32_bf16 v[8:11], v[206:209], v[178:181], v[8:11]
	v_mfma_f32_16x16x32_bf16 v[4:7], v[198:201], v[190:193], v[4:7]
	v_mfma_f32_16x16x32_bf16 v[0:3], v[206:209], v[190:193], v[0:3]
	v_add_u32_e32 v80, 0x18000, v187
	s_barrier
	ds_read_b128 v[130:133], v80
	ds_read_b128 v[134:137], v80 offset:1024
	ds_read_b128 v[138:141], v80 offset:2048
	ds_read_b128 v[142:145], v80 offset:3072
	s_add_u32 vcc_lo, s10, s64
	s_addc_u32 vcc_hi, s11, 0
	s_mov_b32 m0, s99
	ds_read_b128 v[146:149], v189 offset:32768
	ds_read_b128 v[150:153], v189 offset:33792
	ds_read_b128 v[154:157], v189 offset:34816
	ds_read_b128 v[158:161], v189 offset:35840
	ds_read_b128 v[174:177], v189 offset:36864
	ds_read_b128 v[178:181], v189 offset:37888
	ds_read_b128 v[182:185], v189 offset:38912
	ds_read_b128 v[190:193], v189 offset:39936
	global_load_lds_dwordx4 v162, vcc
	s_mov_b32 m0, s33
	ds_read_b128 v[194:197], v80 offset:16384
	ds_read_b128 v[198:201], v80 offset:17408
	ds_read_b128 v[202:205], v80 offset:18432
	ds_read_b128 v[206:209], v80 offset:19456
	global_load_lds_dwordx4 v166, vcc
	s_waitcnt lgkmcnt(0)
	s_waitcnt vmcnt(8)
	s_barrier
	v_mfma_f32_16x16x32_bf16 v[126:129], v[130:133], v[146:149], v[126:129]
	v_mfma_f32_16x16x32_bf16 v[122:125], v[138:141], v[146:149], v[122:125]
	v_mfma_f32_16x16x32_bf16 v[118:121], v[130:133], v[154:157], v[118:121]
	v_mfma_f32_16x16x32_bf16 v[114:117], v[138:141], v[154:157], v[114:117]
	v_mfma_f32_16x16x32_bf16 v[110:113], v[130:133], v[174:177], v[110:113]
	v_mfma_f32_16x16x32_bf16 v[106:109], v[138:141], v[174:177], v[106:109]
	v_mfma_f32_16x16x32_bf16 v[102:105], v[130:133], v[182:185], v[102:105]
	v_mfma_f32_16x16x32_bf16 v[98:101], v[138:141], v[182:185], v[98:101]
	v_mfma_f32_16x16x32_bf16 v[126:129], v[134:137], v[150:153], v[126:129]
	v_mfma_f32_16x16x32_bf16 v[122:125], v[142:145], v[150:153], v[122:125]
	v_mfma_f32_16x16x32_bf16 v[118:121], v[134:137], v[158:161], v[118:121]
	v_mfma_f32_16x16x32_bf16 v[114:117], v[142:145], v[158:161], v[114:117]
	v_mfma_f32_16x16x32_bf16 v[110:113], v[134:137], v[178:181], v[110:113]
	v_mfma_f32_16x16x32_bf16 v[106:109], v[142:145], v[178:181], v[106:109]
	v_mfma_f32_16x16x32_bf16 v[102:105], v[134:137], v[190:193], v[102:105]
	v_mfma_f32_16x16x32_bf16 v[98:101], v[142:145], v[190:193], v[98:101]
	v_mfma_f32_16x16x32_bf16 v[60:63], v[194:197], v[146:149], v[60:63]
	v_mfma_f32_16x16x32_bf16 v[56:59], v[202:205], v[146:149], v[56:59]
	v_mfma_f32_16x16x32_bf16 v[52:55], v[194:197], v[154:157], v[52:55]
	v_mfma_f32_16x16x32_bf16 v[48:51], v[202:205], v[154:157], v[48:51]
	v_mfma_f32_16x16x32_bf16 v[44:47], v[194:197], v[174:177], v[44:47]
	v_mfma_f32_16x16x32_bf16 v[40:43], v[202:205], v[174:177], v[40:43]
	v_mfma_f32_16x16x32_bf16 v[36:39], v[194:197], v[182:185], v[36:39]
	v_mfma_f32_16x16x32_bf16 v[32:35], v[202:205], v[182:185], v[32:35]
	v_mfma_f32_16x16x32_bf16 v[60:63], v[198:201], v[150:153], v[60:63]
	v_mfma_f32_16x16x32_bf16 v[56:59], v[206:209], v[150:153], v[56:59]
	v_mfma_f32_16x16x32_bf16 v[52:55], v[198:201], v[158:161], v[52:55]
	v_mfma_f32_16x16x32_bf16 v[48:51], v[206:209], v[158:161], v[48:51]
	v_mfma_f32_16x16x32_bf16 v[44:47], v[198:201], v[178:181], v[44:47]
	v_mfma_f32_16x16x32_bf16 v[40:43], v[206:209], v[178:181], v[40:43]
	v_mfma_f32_16x16x32_bf16 v[36:39], v[198:201], v[190:193], v[36:39]
	v_mfma_f32_16x16x32_bf16 v[32:35], v[206:209], v[190:193], v[32:35]
	s_barrier
; #define PG8_STAGE(bufoff, gbase, voff) do { _Pragma("unroll") for (int _i = 0; _i < 2; ++_i) \
;     __builtin_amdgcn_global_load_lds((const unsigned*)((const char*)(gbase) + (voff)[_i]), (LAS unsigned*)(lds + (bufoff) + ldsw + _i * 8192), 16, 0, 0); } while (0)
; #define PG8_LDA(dst, b, h) do { _Pragma("unroll") for (int m = 0; m < 4; ++m) _Pragma("unroll") for (int k = 0; k < 2; ++k) dst[m][k] = *(const LAS bf16x8*)(lds + PG8_SA(b, h) + aoff + m * 2048 + k * 1024); } while (0)
; #define PG8_MMA(ai, bj, At, Bt) do { __builtin_amdgcn_s_setprio(1); _Pragma("unroll") for (int m = 0; m < 4; ++m) _Pragma("unroll") for (int n = 0; n < 2; ++n) _Pragma("unroll") for (int k = 0; k < 2; ++k) \
;     acc[ai][bj][m][n] = __builtin_amdgcn_mfma_f32_16x16x32_bf16(Bt[n][k], At[m][k], acc[ai][bj][m][n], 0, 0, 0); __builtin_amdgcn_s_setprio(0); } while (0)
; #define PG8_WAIT_V(n) asm volatile("s_waitcnt vmcnt(" #n ")" ::: "memory")
; #define PG8_WAIT_L(n) asm volatile("s_waitcnt lgkmcnt(" #n ")" ::: "memory")
; #define PG8_BAR __builtin_amdgcn_s_barrier()
; #define PG8_SCHED __builtin_amdgcn_sched_barrier(0)
; template <class Epi>
; __device__ __forceinline__ void gemm_phase(LAS unsigned char* lds, const Gemm g, const StaticOrder& S, const Epi& E) {
;     ...
;       PG8_LDA(At, 1, 1); PG8_STAGE(PG8_SA(1, 0), a3, voffA);
;       PG8_BAR; PG8_WAIT_L(0); PG8_MMA(1, 0, At, B0); PG8_BAR; PG8_SCHED;
;       PG8_STAGE(PG8_SB(1, 1), b3 + hstep, voffB);
;       PG8_WAIT_V(6); PG8_BAR; PG8_MMA(1, 1, At, B1); PG8_BAR;
	ds_read_b128 v[146:149], v189 offset:49152
	ds_read_b128 v[150:153], v189 offset:50176
	ds_read_b128 v[154:157], v189 offset:51200
	ds_read_b128 v[158:161], v189 offset:52224
	ds_read_b128 v[174:177], v189 offset:53248
	ds_read_b128 v[178:181], v189 offset:54272
	ds_read_b128 v[182:185], v189 offset:55296
	ds_read_b128 v[190:193], v189 offset:56320
	s_add_i32 m0, s14, 0x17f80
	s_add_u32 vcc_lo, s12, s64
	s_addc_u32 vcc_hi, s13, 0
	global_load_lds_dwordx4 v164, s[12:13] offset:128
	s_add_i32 m0, s14, 0x19f80
	s_nop 0
	global_load_lds_dwordx4 v168, s[12:13] offset:128
	s_add_i32 m0, s29, 0xffffff80
	s_nop 0
	global_load_lds_dwordx4 v162, s[10:11] offset:128
	s_add_i32 m0, s20, 0xffffff80
	s_nop 0
	global_load_lds_dwordx4 v166, s[10:11] offset:128
	s_add_i32 m0, s14, 0x1bf80
	s_nop 0
	global_load_lds_dwordx4 v164, vcc offset:128
	s_add_i32 m0, s14, 0x1df80
	s_nop 0
	global_load_lds_dwordx4 v168, vcc offset:128
	s_waitcnt lgkmcnt(0)
	s_waitcnt vmcnt(8)
	s_barrier
	v_mfma_f32_16x16x32_bf16 v[94:97], v[130:133], v[146:149], v[94:97]
	v_mfma_f32_16x16x32_bf16 v[90:93], v[138:141], v[146:149], v[90:93]
	v_mfma_f32_16x16x32_bf16 v[86:89], v[130:133], v[154:157], v[86:89]
	v_mfma_f32_16x16x32_bf16 v[82:85], v[138:141], v[154:157], v[82:85]
	v_mfma_f32_16x16x32_bf16 v[76:79], v[130:133], v[174:177], v[76:79]
	v_mfma_f32_16x16x32_bf16 v[72:75], v[138:141], v[174:177], v[72:75]
	v_mfma_f32_16x16x32_bf16 v[68:71], v[130:133], v[182:185], v[68:71]
	v_mfma_f32_16x16x32_bf16 v[64:67], v[138:141], v[182:185], v[64:67]
	v_mfma_f32_16x16x32_bf16 v[94:97], v[134:137], v[150:153], v[94:97]
	v_mfma_f32_16x16x32_bf16 v[90:93], v[142:145], v[150:153], v[90:93]
	v_mfma_f32_16x16x32_bf16 v[86:89], v[134:137], v[158:161], v[86:89]
	v_mfma_f32_16x16x32_bf16 v[82:85], v[142:145], v[158:161], v[82:85]
	v_mfma_f32_16x16x32_bf16 v[76:79], v[134:137], v[178:181], v[76:79]
	v_mfma_f32_16x16x32_bf16 v[72:75], v[142:145], v[178:181], v[72:75]
	v_mfma_f32_16x16x32_bf16 v[68:71], v[134:137], v[190:193], v[68:71]
	v_mfma_f32_16x16x32_bf16 v[64:67], v[142:145], v[190:193], v[64:67]
	v_mfma_f32_16x16x32_bf16 v[28:31], v[194:197], v[146:149], v[28:31]
	v_mfma_f32_16x16x32_bf16 v[24:27], v[202:205], v[146:149], v[24:27]
	v_mfma_f32_16x16x32_bf16 v[20:23], v[194:197], v[154:157], v[20:23]
	v_mfma_f32_16x16x32_bf16 v[16:19], v[202:205], v[154:157], v[16:19]
	v_mfma_f32_16x16x32_bf16 v[12:15], v[194:197], v[174:177], v[12:15]
	v_mfma_f32_16x16x32_bf16 v[8:11], v[202:205], v[174:177], v[8:11]
	v_mfma_f32_16x16x32_bf16 v[4:7], v[194:197], v[182:185], v[4:7]
	v_mfma_f32_16x16x32_bf16 v[0:3], v[202:205], v[182:185], v[0:3]
	v_mfma_f32_16x16x32_bf16 v[28:31], v[198:201], v[150:153], v[28:31]
	v_mfma_f32_16x16x32_bf16 v[24:27], v[206:209], v[150:153], v[24:27]
	v_mfma_f32_16x16x32_bf16 v[20:23], v[198:201], v[158:161], v[20:23]
	v_mfma_f32_16x16x32_bf16 v[16:19], v[206:209], v[158:161], v[16:19]
	v_mfma_f32_16x16x32_bf16 v[12:15], v[198:201], v[178:181], v[12:15]
	v_mfma_f32_16x16x32_bf16 v[8:11], v[206:209], v[178:181], v[8:11]
	v_mfma_f32_16x16x32_bf16 v[4:7], v[198:201], v[190:193], v[4:7]
	v_mfma_f32_16x16x32_bf16 v[0:3], v[206:209], v[190:193], v[0:3]
	s_add_u32 s74, s74, 0x100
	s_addc_u32 s75, s75, 0
	s_add_u32 s0, s0, 0x100
	s_addc_u32 s1, s1, 0
	s_cmp_ge_u32 s76, s2
	s_mov_b32 s10, s76
	s_barrier
	s_cbranch_scc0 .LBB0_56
	s_cmp_lg_u32 s71, 0
	s_cselect_b64 s[0:1], -1, 0
	s_cmp_eq_u32 s71, 0
	s_cselect_b32 s10, s73, s72
	s_cselect_b32 s11, s72, s73
	s_lshl_b32 s71, s10, 8
	s_add_i32 s71, s71, s28
	v_or_b32_e32 v176, s71, v186
	v_lshl_or_b32 v174, s11, 8, v188
	s_cmp_lt_i32 s98, 2
	s_mov_b64 s[10:11], -1
	s_cbranch_scc1 .LBB0_151
	s_cmp_lt_i32 s98, 4
	s_cbranch_scc1 .LBB0_84
	s_cmp_lt_i32 s98, 5
	s_cbranch_scc1 .LBB0_65
	s_cmp_lg_u32 s98, 5
	s_cbranch_scc0 .LBB0_62
	v_readlane_b32 s10, v254, 18
	v_ashrrev_i32_e32 v175, 31, v174
	v_readlane_b32 s11, v254, 19
	v_ashrrev_i32_e32 v177, 31, v176
	v_lshlrev_b64 v[130:131], 11, v[176:177]
	v_lshl_add_u64 v[136:137], v[174:175], 1, s[10:11]
	v_or_b32_e32 v190, 16, v176
	v_lshl_add_u64 v[130:131], v[136:137], 0, v[130:131]
	v_ashrrev_i32_e32 v191, 31, v190
	flat_load_dwordx4 v[138:141], v[130:131]
	flat_load_dwordx4 v[142:145], v[130:131] offset:256
	v_lshlrev_b64 v[130:131], 11, v[190:191]
	v_or_b32_e32 v192, 32, v176
	v_lshl_add_u64 v[130:131], v[136:137], 0, v[130:131]
	v_ashrrev_i32_e32 v193, 31, v192
	flat_load_dwordx4 v[146:149], v[130:131]
	flat_load_dwordx4 v[150:153], v[130:131] offset:256
	v_lshlrev_b64 v[130:131], 11, v[192:193]
	v_or_b32_e32 v194, 48, v176
	v_lshl_add_u64 v[130:131], v[136:137], 0, v[130:131]
	v_ashrrev_i32_e32 v195, 31, v194
	flat_load_dwordx4 v[154:157], v[130:131]
	flat_load_dwordx4 v[158:161], v[130:131] offset:256
	v_lshlrev_b64 v[130:131], 11, v[194:195]
	v_lshl_add_u64 v[130:131], v[136:137], 0, v[130:131]
	flat_load_dwordx4 v[178:181], v[130:131]
	s_nop 0
	flat_load_dwordx4 v[130:133], v[130:131] offset:256
	v_readlane_b32 s10, v254, 20
	v_readlane_b32 s11, v254, 21
	s_nop 1
	v_lshl_add_u64 v[134:135], v[174:175], 2, s[10:11]
	v_lshlrev_b64 v[182:183], 12, v[176:177]
	v_lshl_add_u64 v[196:197], v[134:135], 0, v[182:183]
	s_waitcnt vmcnt(0) lgkmcnt(0)
; __device__ __forceinline__ float lo16(unsigned v) { return __uint_as_float(v << 16); }
; __device__ __forceinline__ float hi16(unsigned v) { return __uint_as_float(v & 0xffff0000u); }
;   __device__ __forceinline__ void operator()(const f32x4 (&acc)[2][2][4][2], const pg8::Unit& u, int wr, int wc, int fr, int fq) const {
;     ...
;       float* xo = P->out + (size_t)slice * TS * DM; const u16* x2b = (const u16*)(ws + O_X2B) + (size_t)slice * TS * DM;
; #pragma unroll
;       for (int ai = 0; ai < 2; ++ai) {
;         u32x4 xv[4][2];
; #pragma unroll
;         for (int m = 0; m < 4; ++m)
; #pragma unroll
;           for (int bj = 0; bj < 2; ++bj) xv[m][bj] = *(const u32x4*)(x2b + (size_t)(row0 + ai * 128 + m * 16) * DM + col0 + bj * 128);
;         __builtin_amdgcn_sched_barrier(0);
; #pragma unroll
;         for (int m = 0; m < 4; ++m) {
;           const int row = row0 + ai * 128 + m * 16;
; #pragma unroll
;           for (int bj = 0; bj < 2; ++bj) {
;             float* d = xo + (size_t)row * DM + col0 + bj * 128;
;             const u32x4 x4 = xv[m][bj];
;             f32x4 o0 = acc[ai][bj][m][0], o1 = acc[ai][bj][m][1];
;             o0[0] += lo16(x4.x); o0[1] += hi16(x4.x); o0[2] += lo16(x4.y); o0[3] += hi16(x4.y); o1[0] += lo16(x4.z); o1[1] += hi16(x4.z); o1[2] += lo16(x4.w); o1[3] += hi16(x4.w);
;             *(f32x4*)d = o0; *(f32x4*)(d + 4) = o1;
;           }
;         }
	v_lshlrev_b32_e32 v182, 16, v138
	v_and_b32_e32 v183, 0xffff0000, v138
	v_lshlrev_b32_e32 v138, 16, v139
	v_and_b32_e32 v139, 0xffff0000, v139
	v_pk_add_f32 v[184:185], v[128:129], v[138:139]
	v_lshlrev_b32_e32 v138, 16, v140
	v_and_b32_e32 v139, 0xffff0000, v140
	v_lshlrev_b32_e32 v140, 16, v141
	v_and_b32_e32 v141, 0xffff0000, v141
	v_pk_add_f32 v[182:183], v[126:127], v[182:183]
	v_pk_add_f32 v[138:139], v[122:123], v[138:139]
	v_pk_add_f32 v[140:141], v[124:125], v[140:141]
	global_store_dwordx4 v[196:197], v[182:185], off
	global_store_dwordx4 v[196:197], v[138:141], off offset:16
	s_nop 1
	v_lshlrev_b32_e32 v138, 16, v142
	v_and_b32_e32 v139, 0xffff0000, v142
	v_lshlrev_b32_e32 v140, 16, v143
	v_and_b32_e32 v141, 0xffff0000, v143
	v_pk_add_f32 v[138:139], v[60:61], v[138:139]
	v_pk_add_f32 v[140:141], v[62:63], v[140:141]
	v_lshlrev_b32_e32 v142, 16, v144
	v_and_b32_e32 v143, 0xffff0000, v144
	v_lshlrev_b32_e32 v144, 16, v145
	v_and_b32_e32 v145, 0xffff0000, v145
	v_pk_add_f32 v[142:143], v[56:57], v[142:143]
	v_pk_add_f32 v[144:145], v[58:59], v[144:145]
	global_store_dwordx4 v[196:197], v[138:141], off offset:512
	global_store_dwordx4 v[196:197], v[142:145], off offset:528
	s_nop 0
	v_lshlrev_b64 v[138:139], 12, v[190:191]
	v_lshl_add_u64 v[182:183], v[134:135], 0, v[138:139]
	v_lshlrev_b32_e32 v138, 16, v146
	v_and_b32_e32 v139, 0xffff0000, v146
	v_lshlrev_b32_e32 v140, 16, v147
	v_and_b32_e32 v141, 0xffff0000, v147
	v_pk_add_f32 v[138:139], v[118:119], v[138:139]
	v_pk_add_f32 v[140:141], v[120:121], v[140:141]
	v_lshlrev_b32_e32 v142, 16, v148
	v_and_b32_e32 v143, 0xffff0000, v148
	v_lshlrev_b32_e32 v144, 16, v149
	v_and_b32_e32 v145, 0xffff0000, v149
	v_pk_add_f32 v[142:143], v[114:115], v[142:143]
	v_pk_add_f32 v[144:145], v[116:117], v[144:145]
	global_store_dwordx4 v[182:183], v[138:141], off
	global_store_dwordx4 v[182:183], v[142:145], off offset:16
	s_nop 0
	v_lshlrev_b32_e32 v138, 16, v150
	v_and_b32_e32 v139, 0xffff0000, v150
	v_lshlrev_b32_e32 v140, 16, v151
	v_and_b32_e32 v141, 0xffff0000, v151
	v_pk_add_f32 v[138:139], v[52:53], v[138:139]
	v_pk_add_f32 v[140:141], v[54:55], v[140:141]
	v_lshlrev_b32_e32 v142, 16, v152
	v_and_b32_e32 v143, 0xffff0000, v152
	v_lshlrev_b32_e32 v144, 16, v153
	v_and_b32_e32 v145, 0xffff0000, v153
	v_pk_add_f32 v[142:143], v[48:49], v[142:143]
	v_pk_add_f32 v[144:145], v[50:51], v[144:145]
	global_store_dwordx4 v[182:183], v[138:141], off offset:512
	global_store_dwordx4 v[182:183], v[142:145], off offset:528
	s_nop 0
	v_lshlrev_b64 v[138:139], 12, v[192:193]
	v_lshl_add_u64 v[146:147], v[134:135], 0, v[138:139]
	v_lshlrev_b32_e32 v138, 16, v154
	v_and_b32_e32 v139, 0xffff0000, v154
	v_lshlrev_b32_e32 v140, 16, v155
	v_and_b32_e32 v141, 0xffff0000, v155
	v_pk_add_f32 v[138:139], v[110:111], v[138:139]
	v_pk_add_f32 v[140:141], v[112:113], v[140:141]
	v_lshlrev_b32_e32 v142, 16, v156
	v_and_b32_e32 v143, 0xffff0000, v156
	v_lshlrev_b32_e32 v144, 16, v157
	v_and_b32_e32 v145, 0xffff0000, v157
	v_pk_add_f32 v[142:143], v[106:107], v[142:143]
	v_pk_add_f32 v[144:145], v[108:109], v[144:145]
	global_store_dwordx4 v[146:147], v[138:141], off
	global_store_dwordx4 v[146:147], v[142:145], off offset:16
	s_nop 0
	v_lshlrev_b32_e32 v138, 16, v158
	v_and_b32_e32 v139, 0xffff0000, v158
	v_lshlrev_b32_e32 v140, 16, v159
	v_and_b32_e32 v141, 0xffff0000, v159
	v_pk_add_f32 v[138:139], v[44:45], v[138:139]
	v_pk_add_f32 v[140:141], v[46:47], v[140:141]
	v_lshlrev_b32_e32 v142, 16, v160
	v_and_b32_e32 v143, 0xffff0000, v160
	v_lshlrev_b32_e32 v144, 16, v161
	v_and_b32_e32 v145, 0xffff0000, v161
	v_pk_add_f32 v[142:143], v[40:41], v[142:143]
	v_pk_add_f32 v[144:145], v[42:43], v[144:145]
	global_store_dwordx4 v[146:147], v[138:141], off offset:512
	global_store_dwordx4 v[146:147], v[142:145], off offset:528
	s_nop 0
	v_lshlrev_b64 v[138:139], 12, v[194:195]
	v_lshl_add_u64 v[146:147], v[134:135], 0, v[138:139]
	v_lshlrev_b32_e32 v138, 16, v178
	v_and_b32_e32 v139, 0xffff0000, v178
	v_lshlrev_b32_e32 v140, 16, v179
	v_and_b32_e32 v141, 0xffff0000, v179
	v_pk_add_f32 v[138:139], v[102:103], v[138:139]
	v_pk_add_f32 v[140:141], v[104:105], v[140:141]
	v_lshlrev_b32_e32 v142, 16, v180
	v_and_b32_e32 v143, 0xffff0000, v180
	v_lshlrev_b32_e32 v144, 16, v181
	v_and_b32_e32 v145, 0xffff0000, v181
	v_pk_add_f32 v[142:143], v[98:99], v[142:143]
	v_pk_add_f32 v[144:145], v[100:101], v[144:145]
	global_store_dwordx4 v[146:147], v[138:141], off
	global_store_dwordx4 v[146:147], v[142:145], off offset:16
	s_nop 0
	v_lshlrev_b32_e32 v138, 16, v130
	v_and_b32_e32 v139, 0xffff0000, v130
	v_lshlrev_b32_e32 v130, 16, v131
	v_and_b32_e32 v131, 0xffff0000, v131
	v_pk_add_f32 v[138:139], v[36:37], v[138:139]
	v_pk_add_f32 v[140:141], v[38:39], v[130:131]
	v_lshlrev_b32_e32 v130, 16, v132
	v_and_b32_e32 v131, 0xffff0000, v132
	v_lshlrev_b32_e32 v132, 16, v133
	v_and_b32_e32 v133, 0xffff0000, v133
	v_pk_add_f32 v[130:131], v[32:33], v[130:131]
	v_pk_add_f32 v[132:133], v[34:35], v[132:133]
	global_store_dwordx4 v[146:147], v[138:141], off offset:512
	global_store_dwordx4 v[146:147], v[130:133], off offset:528
	v_add_u32_e32 v182, 0x80, v176
	v_ashrrev_i32_e32 v183, 31, v182
	v_lshlrev_b64 v[130:131], 11, v[182:183]
	v_add_u32_e32 v190, 0x90, v176
	v_lshl_add_u64 v[130:131], v[136:137], 0, v[130:131]
	v_ashrrev_i32_e32 v191, 31, v190
	flat_load_dwordx4 v[138:141], v[130:131]
	flat_load_dwordx4 v[142:145], v[130:131] offset:256
	v_lshlrev_b64 v[130:131], 11, v[190:191]
	v_add_u32_e32 v192, 0xa0, v176
	v_lshl_add_u64 v[130:131], v[136:137], 0, v[130:131]
	v_ashrrev_i32_e32 v193, 31, v192
	flat_load_dwordx4 v[146:149], v[130:131]
	flat_load_dwordx4 v[150:153], v[130:131] offset:256
	v_lshlrev_b64 v[130:131], 11, v[192:193]
	v_add_u32_e32 v194, 0xb0, v176
	v_lshl_add_u64 v[130:131], v[136:137], 0, v[130:131]
	v_ashrrev_i32_e32 v195, 31, v194
	flat_load_dwordx4 v[154:157], v[130:131]
	flat_load_dwordx4 v[158:161], v[130:131] offset:256
	v_lshlrev_b64 v[130:131], 11, v[194:195]
	v_lshl_add_u64 v[130:131], v[136:137], 0, v[130:131]
	flat_load_dwordx4 v[178:181], v[130:131]
	s_nop 0
	flat_load_dwordx4 v[130:133], v[130:131] offset:256
	v_lshlrev_b64 v[136:137], 12, v[182:183]
	v_lshl_add_u64 v[196:197], v[134:135], 0, v[136:137]
	s_waitcnt vmcnt(0) lgkmcnt(0)
; __device__ __forceinline__ float lo16(unsigned v) { return __uint_as_float(v << 16); }
; __device__ __forceinline__ float hi16(unsigned v) { return __uint_as_float(v & 0xffff0000u); }
;   __device__ __forceinline__ void operator()(const f32x4 (&acc)[2][2][4][2], const pg8::Unit& u, int wr, int wc, int fr, int fq) const {
;     ...
; #pragma unroll
;         for (int m = 0; m < 4; ++m) {
;           const int row = row0 + ai * 128 + m * 16;
; #pragma unroll
;           for (int bj = 0; bj < 2; ++bj) {
;             float* d = xo + (size_t)row * DM + col0 + bj * 128;
;             const u32x4 x4 = xv[m][bj];
;             f32x4 o0 = acc[ai][bj][m][0], o1 = acc[ai][bj][m][1];
;             o0[0] += lo16(x4.x); o0[1] += hi16(x4.x); o0[2] += lo16(x4.y); o0[3] += hi16(x4.y); o1[0] += lo16(x4.z); o1[1] += hi16(x4.z); o1[2] += lo16(x4.w); o1[3] += hi16(x4.w);
;             *(f32x4*)d = o0; *(f32x4*)(d + 4) = o1;
;           }
;         }
	v_lshlrev_b32_e32 v136, 16, v138
	v_and_b32_e32 v137, 0xffff0000, v138
	v_lshlrev_b32_e32 v138, 16, v139
	v_and_b32_e32 v139, 0xffff0000, v139
	v_pk_add_f32 v[136:137], v[94:95], v[136:137]
	v_pk_add_f32 v[138:139], v[96:97], v[138:139]
	v_lshlrev_b32_e32 v182, 16, v140
	v_and_b32_e32 v183, 0xffff0000, v140
	v_lshlrev_b32_e32 v140, 16, v141
	v_and_b32_e32 v141, 0xffff0000, v141
	v_pk_add_f32 v[182:183], v[90:91], v[182:183]
	v_pk_add_f32 v[184:185], v[92:93], v[140:141]
	global_store_dwordx4 v[196:197], v[136:139], off
	global_store_dwordx4 v[196:197], v[182:185], off offset:16
	v_lshlrev_b32_e32 v140, 16, v144
	v_lshlrev_b32_e32 v136, 16, v142
	v_and_b32_e32 v137, 0xffff0000, v142
	v_lshlrev_b32_e32 v138, 16, v143
	v_and_b32_e32 v139, 0xffff0000, v143
	v_pk_add_f32 v[136:137], v[28:29], v[136:137]
	v_pk_add_f32 v[138:139], v[30:31], v[138:139]
	v_and_b32_e32 v141, 0xffff0000, v144
	v_lshlrev_b32_e32 v142, 16, v145
	v_and_b32_e32 v143, 0xffff0000, v145
	v_pk_add_f32 v[140:141], v[24:25], v[140:141]
	v_pk_add_f32 v[142:143], v[26:27], v[142:143]
	global_store_dwordx4 v[196:197], v[136:139], off offset:512
	global_store_dwordx4 v[196:197], v[140:143], off offset:528
	s_nop 0
	v_lshlrev_b64 v[136:137], 12, v[190:191]
	v_lshl_add_u64 v[144:145], v[134:135], 0, v[136:137]
	v_lshlrev_b32_e32 v136, 16, v146
	v_and_b32_e32 v137, 0xffff0000, v146
	v_lshlrev_b32_e32 v138, 16, v147
	v_and_b32_e32 v139, 0xffff0000, v147
	v_pk_add_f32 v[136:137], v[86:87], v[136:137]
	v_pk_add_f32 v[138:139], v[88:89], v[138:139]
	v_lshlrev_b32_e32 v140, 16, v148
	v_and_b32_e32 v141, 0xffff0000, v148
	v_lshlrev_b32_e32 v142, 16, v149
	v_and_b32_e32 v143, 0xffff0000, v149
	v_pk_add_f32 v[140:141], v[82:83], v[140:141]
	v_pk_add_f32 v[142:143], v[84:85], v[142:143]
	global_store_dwordx4 v[144:145], v[136:139], off
	global_store_dwordx4 v[144:145], v[140:143], off offset:16
	s_nop 0
	v_lshlrev_b32_e32 v136, 16, v150
	v_and_b32_e32 v137, 0xffff0000, v150
	v_lshlrev_b32_e32 v138, 16, v151
	v_and_b32_e32 v139, 0xffff0000, v151
	v_pk_add_f32 v[136:137], v[20:21], v[136:137]
	v_pk_add_f32 v[138:139], v[22:23], v[138:139]
	v_lshlrev_b32_e32 v140, 16, v152
	v_and_b32_e32 v141, 0xffff0000, v152
	v_lshlrev_b32_e32 v142, 16, v153
	v_and_b32_e32 v143, 0xffff0000, v153
	v_pk_add_f32 v[140:141], v[16:17], v[140:141]
	v_pk_add_f32 v[142:143], v[18:19], v[142:143]
	global_store_dwordx4 v[144:145], v[136:139], off offset:512
	global_store_dwordx4 v[144:145], v[140:143], off offset:528
	s_nop 0
	v_lshlrev_b64 v[136:137], 12, v[192:193]
	v_lshl_add_u64 v[144:145], v[134:135], 0, v[136:137]
	v_lshlrev_b32_e32 v136, 16, v154
	v_and_b32_e32 v137, 0xffff0000, v154
	v_lshlrev_b32_e32 v138, 16, v155
	v_and_b32_e32 v139, 0xffff0000, v155
	v_pk_add_f32 v[136:137], v[76:77], v[136:137]
	v_pk_add_f32 v[138:139], v[78:79], v[138:139]
	v_lshlrev_b32_e32 v140, 16, v156
	v_and_b32_e32 v141, 0xffff0000, v156
	v_lshlrev_b32_e32 v142, 16, v157
	v_and_b32_e32 v143, 0xffff0000, v157
	v_pk_add_f32 v[140:141], v[72:73], v[140:141]
	v_pk_add_f32 v[142:143], v[74:75], v[142:143]
	global_store_dwordx4 v[144:145], v[136:139], off
	global_store_dwordx4 v[144:145], v[140:143], off offset:16
	s_nop 0
	v_lshlrev_b32_e32 v136, 16, v158
	v_and_b32_e32 v137, 0xffff0000, v158
	v_lshlrev_b32_e32 v138, 16, v159
	v_and_b32_e32 v139, 0xffff0000, v159
	v_pk_add_f32 v[136:137], v[12:13], v[136:137]
	v_pk_add_f32 v[138:139], v[14:15], v[138:139]
	v_lshlrev_b32_e32 v140, 16, v160
	v_and_b32_e32 v141, 0xffff0000, v160
	v_lshlrev_b32_e32 v142, 16, v161
	v_and_b32_e32 v143, 0xffff0000, v161
	v_pk_add_f32 v[140:141], v[8:9], v[140:141]
	v_pk_add_f32 v[142:143], v[10:11], v[142:143]
	global_store_dwordx4 v[144:145], v[136:139], off offset:512
	global_store_dwordx4 v[144:145], v[140:143], off offset:528
	s_nop 0
	v_lshlrev_b64 v[136:137], 12, v[194:195]
	v_lshl_add_u64 v[142:143], v[134:135], 0, v[136:137]
	v_lshlrev_b32_e32 v134, 16, v178
	v_and_b32_e32 v135, 0xffff0000, v178
	v_lshlrev_b32_e32 v136, 16, v179
	v_and_b32_e32 v137, 0xffff0000, v179
	v_pk_add_f32 v[134:135], v[68:69], v[134:135]
	v_pk_add_f32 v[136:137], v[70:71], v[136:137]
	v_lshlrev_b32_e32 v138, 16, v180
	v_and_b32_e32 v139, 0xffff0000, v180
	v_lshlrev_b32_e32 v140, 16, v181
	v_and_b32_e32 v141, 0xffff0000, v181
	v_pk_add_f32 v[138:139], v[64:65], v[138:139]
	v_pk_add_f32 v[140:141], v[66:67], v[140:141]
	global_store_dwordx4 v[142:143], v[134:137], off
	global_store_dwordx4 v[142:143], v[138:141], off offset:16
	s_nop 0
	v_lshlrev_b32_e32 v134, 16, v130
	v_and_b32_e32 v135, 0xffff0000, v130
	v_lshlrev_b32_e32 v130, 16, v131
	v_and_b32_e32 v131, 0xffff0000, v131
	v_pk_add_f32 v[134:135], v[4:5], v[134:135]
	v_pk_add_f32 v[136:137], v[6:7], v[130:131]
	v_lshlrev_b32_e32 v130, 16, v132
	v_and_b32_e32 v131, 0xffff0000, v132
	v_lshlrev_b32_e32 v132, 16, v133
	v_and_b32_e32 v133, 0xffff0000, v133
	v_pk_add_f32 v[130:131], v[0:1], v[130:131]
	v_pk_add_f32 v[132:133], v[2:3], v[132:133]
	global_store_dwordx4 v[142:143], v[134:137], off offset:512
	global_store_dwordx4 v[142:143], v[130:133], off offset:528
	s_mov_b64 s[10:11], 0
